# barriers: L1 invalidate issued before the poll loop (all waves of the block idle at the workgroup barrier), overlapping the wait
# speedup vs baseline: 1.0200x; 1.0071x over previous
.LBB0_118:
	s_cmp_gt_i32 s97, 1
	s_cselect_b64 s[0:1], -1, 0
	s_and_b64 s[4:5], s[40:41], s[0:1]
	s_andn2_b64 vcc, exec, s[4:5]
	s_mov_b32 s88, s38
	s_mov_b32 s89, s39
	s_cbranch_vccnz .LBB0_172
	s_waitcnt vmcnt(0) lgkmcnt(0)
	s_barrier
	s_mov_b64 s[4:5], exec
	v_readlane_b32 s6, v254, 2
	v_readlane_b32 s7, v254, 3
	s_nop 1
	s_and_b64 s[6:7], s[4:5], s[6:7]
	s_mov_b64 exec, s[6:7]
	s_cbranch_execz .Lp0_wait_join
	v_mov_b32_e32 v1, 0x23fc4
	ds_read_b32 v2, v1
	s_add_u32 s8, s62, 0x40d800
	s_addc_u32 s9, s63, 0
	v_mov_b32_e32 v1, 0x400
	s_mov_b32 s10, 0
	buffer_inv sc1

.Lp0_spin_done:
.Lp0_wait_join:
	s_mov_b64 exec, s[4:5]
	s_barrier

.Llb182_poll:
	s_mov_b32 s9, 0
	buffer_inv sc1

.Llb287_done:
.Llb287_join:
	s_mov_b64 exec, s[0:1]
	s_barrier

.LBB0_393:
	s_cmp_gt_i32 s97, 4
	s_cselect_b64 s[0:1], -1, 0
	s_and_b64 s[4:5], s[8:9], s[0:1]
	v_readlane_b32 s72, v254, 22
	s_andn2_b64 vcc, exec, s[4:5]
	v_readlane_b32 s82, v254, 32
	v_readlane_b32 s83, v254, 33
	v_readlane_b32 s86, v254, 36
	v_readlane_b32 s87, v254, 37
	v_readlane_b32 s73, v254, 23
	v_readlane_b32 s74, v254, 24
	v_readlane_b32 s75, v254, 25
	v_readlane_b32 s76, v254, 26
	v_readlane_b32 s77, v254, 27
	v_readlane_b32 s78, v254, 28
	v_readlane_b32 s79, v254, 29
	v_readlane_b32 s80, v254, 30
	v_readlane_b32 s81, v254, 31
	v_readlane_b32 s84, v254, 34
	v_readlane_b32 s85, v254, 35
	s_cbranch_vccnz .LBB0_447
	s_waitcnt vmcnt(0) lgkmcnt(0)
	s_barrier
	s_mov_b64 s[4:5], exec
	v_readlane_b32 s6, v254, 2
	v_readlane_b32 s7, v254, 3
	s_nop 1
	s_and_b64 s[6:7], s[4:5], s[6:7]
	s_mov_b64 exec, s[6:7]
	s_cbranch_execz .Lp3_wait_join
	v_mov_b32_e32 v1, 0x23fc0
	ds_read_b64 v[16:17], v1
	s_add_u32 s10, s62, 0x40e000
	s_addc_u32 s11, s63, 0
	v_mov_b32_e32 v1, 0x400
	s_mov_b32 s8, 0
	buffer_inv sc1

.Llb487_poll:
	s_mov_b32 s6, 0
	buffer_inv sc1

.Llb577_poll:
	s_mov_b32 s8, 0
	buffer_inv sc1

.LBB0_638:
	s_cmp_gt_u32 s97, 8
	s_cselect_b64 s[0:1], -1, 0
	s_and_b64 s[0:1], s[4:5], s[0:1]
	s_mov_b64 s[50:51], s[96:97]
	s_andn2_b64 vcc, exec, s[0:1]
	s_cbranch_vccnz .LBB0_693
	s_waitcnt vmcnt(0) lgkmcnt(0)
	s_barrier
	s_mov_b64 s[0:1], exec
	v_readlane_b32 s4, v254, 2
	v_readlane_b32 s5, v254, 3
	s_nop 1
	s_and_b64 s[4:5], s[0:1], s[4:5]
	s_mov_b64 exec, s[4:5]
	s_cbranch_execz .Lr3_wait_join
	v_mov_b32_e32 v1, 0x23fc4
	ds_read_b32 v2, v1
	s_add_u32 s6, s62, 0x409800
	s_addc_u32 s7, s63, 0
	v_mov_b32_e32 v1, 0x400
	s_mov_b32 s8, 0
	buffer_inv sc1

.Llb715_poll:
	s_mov_b32 s16, 0
	buffer_inv sc1

.Llb715_done:
.Llb715_join:
	s_mov_b64 exec, s[8:9]
	s_barrier
